# speedup vs baseline: 1.0634x; 1.0179x over previous
; __device__ __forceinline__ void attn_phase(const Params& p, int o, char* smem) {
;     ...
;     for (int q = 0; q < 8; ++q) {
;       const int tokl = 8 * w + q;
;       const int jb = lane;
;       const float imp = impA[tokl * 64 + jb] + impB[tokl * 64 + jb];
;       const bool valid = jb <= cur;
;       const bool forced = (jb == 0) || (jb == cur) || (jb == cur - 1);
;       float sc = valid ? (forced ? 1e4f : imp) : -1.0f;
;       u64 msk = 0;
;       for (int r = 0; r < 8; ++r) {
;         float mx = sc;
; #pragma unroll
;         for (int s = 32; s >= 1; s >>= 1) mx = fmaxf(mx, __shfl_xor(mx, s));
;         const u64 bal = __ballot(sc == mx);
;         const int ix = __ffsll((long long)bal) - 1;
;         msk |= 1ull << ix;
;         if (lane == ix) sc = -3.0e38f;
;       }
;       if (lane == 0) sel[tokl] = msk;
;     }
.LBB0_633:
	v_add_u32_e32 v51, 0xffffc000, v50
	ds_read_b32 v51, v51
	ds_read_b32 v52, v50
	s_waitcnt lgkmcnt(0)
	v_add_f32_e32 v51, v51, v52
	v_cndmask_b32_e64 v51, v51, v213, s[4:5]
	v_cndmask_b32_e64 v51, v51, -1.0, vcc
	s_nop 1
	v_max_f32_dpp v52, v51, v51 quad_perm:[1,0,3,2] row_mask:0xf bank_mask:0xf
	s_nop 1
	v_max_f32_dpp v52, v52, v52 quad_perm:[2,3,0,1] row_mask:0xf bank_mask:0xf
	s_nop 1
	v_max_f32_dpp v52, v52, v52 row_half_mirror row_mask:0xf bank_mask:0xf
	s_nop 1
	v_max_f32_dpp v52, v52, v52 row_mirror row_mask:0xf bank_mask:0xf
	s_nop 1
	v_max_f32_dpp v52, v52, v52 row_bcast:15 row_mask:0xa bank_mask:0xf
	s_nop 1
	v_max_f32_dpp v52, v52, v52 row_bcast:31 row_mask:0xc bank_mask:0xf
	s_nop 0
	v_readlane_b32 s0, v52, 63
	s_nop 1
	v_cmp_eq_f32_e64 s[6:7], s0, v51
	s_ff1_i32_b64 s0, s[6:7]
	s_cmp_lg_u64 s[6:7], 0
	s_cselect_b32 s9, s0, -1
	v_cmp_ne_u32_e64 s[6:7], s9, v80
	s_nop 1
	v_cndmask_b32_e64 v51, v214, v51, s[6:7]
	s_nop 1
	v_max_f32_dpp v52, v51, v51 quad_perm:[1,0,3,2] row_mask:0xf bank_mask:0xf
	s_nop 1
	v_max_f32_dpp v52, v52, v52 quad_perm:[2,3,0,1] row_mask:0xf bank_mask:0xf
	s_nop 1
	v_max_f32_dpp v52, v52, v52 row_half_mirror row_mask:0xf bank_mask:0xf
	s_nop 1
	v_max_f32_dpp v52, v52, v52 row_mirror row_mask:0xf bank_mask:0xf
	s_nop 1
	v_max_f32_dpp v52, v52, v52 row_bcast:15 row_mask:0xa bank_mask:0xf
	s_nop 1
	v_max_f32_dpp v52, v52, v52 row_bcast:31 row_mask:0xc bank_mask:0xf
	s_nop 0
	v_readlane_b32 s0, v52, 63
	s_nop 1
	v_cmp_eq_f32_e64 s[6:7], s0, v51
	s_ff1_i32_b64 s0, s[6:7]
	s_cmp_lg_u64 s[6:7], 0
	s_cselect_b32 s10, s0, -1
	v_cmp_ne_u32_e64 s[6:7], s10, v80
	s_nop 1
	v_cndmask_b32_e64 v51, v214, v51, s[6:7]
	s_nop 1
	v_max_f32_dpp v52, v51, v51 quad_perm:[1,0,3,2] row_mask:0xf bank_mask:0xf
	s_nop 1
	v_max_f32_dpp v52, v52, v52 quad_perm:[2,3,0,1] row_mask:0xf bank_mask:0xf
	s_nop 1
	v_max_f32_dpp v52, v52, v52 row_half_mirror row_mask:0xf bank_mask:0xf
	s_nop 1
	v_max_f32_dpp v52, v52, v52 row_mirror row_mask:0xf bank_mask:0xf
	s_nop 1
	v_max_f32_dpp v52, v52, v52 row_bcast:15 row_mask:0xa bank_mask:0xf
	s_nop 1
	v_max_f32_dpp v52, v52, v52 row_bcast:31 row_mask:0xc bank_mask:0xf
	s_nop 0
	v_readlane_b32 s0, v52, 63
	s_nop 1
	v_cmp_eq_f32_e64 s[6:7], s0, v51
	s_ff1_i32_b64 s0, s[6:7]
	s_cmp_lg_u64 s[6:7], 0
	s_cselect_b32 s11, s0, -1
	v_cmp_ne_u32_e64 s[6:7], s11, v80
	s_nop 1
	v_cndmask_b32_e64 v51, v214, v51, s[6:7]
	s_nop 1
	v_max_f32_dpp v52, v51, v51 quad_perm:[1,0,3,2] row_mask:0xf bank_mask:0xf
	s_nop 1
	v_max_f32_dpp v52, v52, v52 quad_perm:[2,3,0,1] row_mask:0xf bank_mask:0xf
	s_nop 1
	v_max_f32_dpp v52, v52, v52 row_half_mirror row_mask:0xf bank_mask:0xf
	s_nop 1
	v_max_f32_dpp v52, v52, v52 row_mirror row_mask:0xf bank_mask:0xf
	s_nop 1
	v_max_f32_dpp v52, v52, v52 row_bcast:15 row_mask:0xa bank_mask:0xf
	s_nop 1
	v_max_f32_dpp v52, v52, v52 row_bcast:31 row_mask:0xc bank_mask:0xf
	s_nop 0
	v_readlane_b32 s0, v52, 63
	s_nop 1
	v_cmp_eq_f32_e64 s[6:7], s0, v51
	s_ff1_i32_b64 s0, s[6:7]
	s_cmp_lg_u64 s[6:7], 0
	s_cselect_b32 s12, s0, -1
	v_cmp_ne_u32_e64 s[6:7], s12, v80
	s_nop 1
	v_cndmask_b32_e64 v51, v214, v51, s[6:7]
	s_nop 1
	v_max_f32_dpp v52, v51, v51 quad_perm:[1,0,3,2] row_mask:0xf bank_mask:0xf
	s_nop 1
	v_max_f32_dpp v52, v52, v52 quad_perm:[2,3,0,1] row_mask:0xf bank_mask:0xf
	s_nop 1
	v_max_f32_dpp v52, v52, v52 row_half_mirror row_mask:0xf bank_mask:0xf
	s_nop 1
	v_max_f32_dpp v52, v52, v52 row_mirror row_mask:0xf bank_mask:0xf
	s_nop 1
	v_max_f32_dpp v52, v52, v52 row_bcast:15 row_mask:0xa bank_mask:0xf
	s_nop 1
	v_max_f32_dpp v52, v52, v52 row_bcast:31 row_mask:0xc bank_mask:0xf
	s_nop 0
	v_readlane_b32 s0, v52, 63
	s_nop 1
	v_cmp_eq_f32_e64 s[6:7], s0, v51
	s_ff1_i32_b64 s0, s[6:7]
	s_cmp_lg_u64 s[6:7], 0
	s_cselect_b32 s13, s0, -1
	v_cmp_ne_u32_e64 s[6:7], s13, v80
	s_nop 1
	v_cndmask_b32_e64 v51, v214, v51, s[6:7]
	s_nop 1
	v_max_f32_dpp v52, v51, v51 quad_perm:[1,0,3,2] row_mask:0xf bank_mask:0xf
	s_nop 1
	v_max_f32_dpp v52, v52, v52 quad_perm:[2,3,0,1] row_mask:0xf bank_mask:0xf
	s_nop 1
	v_max_f32_dpp v52, v52, v52 row_half_mirror row_mask:0xf bank_mask:0xf
	s_nop 1
	v_max_f32_dpp v52, v52, v52 row_mirror row_mask:0xf bank_mask:0xf
	s_nop 1
	v_max_f32_dpp v52, v52, v52 row_bcast:15 row_mask:0xa bank_mask:0xf
	s_nop 1
	v_max_f32_dpp v52, v52, v52 row_bcast:31 row_mask:0xc bank_mask:0xf
	s_nop 0
	v_readlane_b32 s0, v52, 63
	s_nop 1
	v_cmp_eq_f32_e64 s[6:7], s0, v51
	s_ff1_i32_b64 s0, s[6:7]
	s_cmp_lg_u64 s[6:7], 0
	s_cselect_b32 s14, s0, -1
	v_cmp_ne_u32_e64 s[6:7], s14, v80
	s_nop 1
	v_cndmask_b32_e64 v51, v214, v51, s[6:7]
	s_nop 1
	v_max_f32_dpp v52, v51, v51 quad_perm:[1,0,3,2] row_mask:0xf bank_mask:0xf
	s_nop 1
	v_max_f32_dpp v52, v52, v52 quad_perm:[2,3,0,1] row_mask:0xf bank_mask:0xf
	s_nop 1
	v_max_f32_dpp v52, v52, v52 row_half_mirror row_mask:0xf bank_mask:0xf
	s_nop 1
	v_max_f32_dpp v52, v52, v52 row_mirror row_mask:0xf bank_mask:0xf
	s_nop 1
	v_max_f32_dpp v52, v52, v52 row_bcast:15 row_mask:0xa bank_mask:0xf
	s_nop 1
	v_max_f32_dpp v52, v52, v52 row_bcast:31 row_mask:0xc bank_mask:0xf
	s_nop 0
	v_readlane_b32 s0, v52, 63
	s_nop 1
	v_cmp_eq_f32_e64 s[6:7], s0, v51
	s_ff1_i32_b64 s0, s[6:7]
	s_cmp_lg_u64 s[6:7], 0
	s_cselect_b32 s15, s0, -1
	v_cmp_ne_u32_e64 s[6:7], s15, v80
	s_nop 1
	v_cndmask_b32_e64 v51, v214, v51, s[6:7]
	s_nop 1
	v_max_f32_dpp v52, v51, v51 quad_perm:[1,0,3,2] row_mask:0xf bank_mask:0xf
	s_nop 1
	v_max_f32_dpp v52, v52, v52 quad_perm:[2,3,0,1] row_mask:0xf bank_mask:0xf
	s_nop 1
	v_max_f32_dpp v52, v52, v52 row_half_mirror row_mask:0xf bank_mask:0xf
	s_nop 1
	v_max_f32_dpp v52, v52, v52 row_mirror row_mask:0xf bank_mask:0xf
	s_nop 1
	v_max_f32_dpp v52, v52, v52 row_bcast:15 row_mask:0xa bank_mask:0xf
	s_nop 1
	v_max_f32_dpp v52, v52, v52 row_bcast:31 row_mask:0xc bank_mask:0xf
	s_nop 0
	v_readlane_b32 s0, v52, 63
	s_nop 1
	v_cmp_eq_f32_e64 s[6:7], s0, v51
	s_and_saveexec_b64 s[0:1], s[2:3]
	s_cbranch_execz .LBB0_632
	s_sub_u32 s16, 0, s6
	s_subb_u32 s17, 0, s7
	s_lshl_b64 s[20:21], 1, s11
	s_lshl_b64 s[10:11], 1, s10
	s_lshl_b64 s[22:23], 1, s9
	s_or_b64 s[10:11], s[10:11], s[22:23]
	s_lshl_b64 s[18:19], 1, s13
	s_lshl_b64 s[12:13], 1, s12
	s_or_b64 s[10:11], s[10:11], s[20:21]
	s_or_b64 s[10:11], s[10:11], s[12:13]
	s_and_b64 s[6:7], s[6:7], s[16:17]
	s_lshl_b64 s[16:17], 1, s15
	s_lshl_b64 s[14:15], 1, s14
	s_or_b64 s[10:11], s[10:11], s[18:19]
	s_or_b64 s[10:11], s[10:11], s[14:15]
	s_or_b64 s[10:11], s[10:11], s[16:17]
	s_or_b64 s[6:7], s[10:11], s[6:7]
	v_add_u32_e32 v51, s8, v49
	v_mov_b64_e32 v[52:53], s[6:7]
	ds_write_b64 v51, v[52:53]
	s_branch .LBB0_632
